# group barriers (32 workgroups sharing blockIdx%8) at seam 4 (attention/gMLP -> Wout, phase 4 items re-mapped so each group owns 2 batches) and seam 6 (FF1 -> FF2); seam 5 stays grid-wide because FF1 o
# speedup vs baseline: 1.0132x; 1.0051x over previous
; __device__ __forceinline__ void phase4_attn(const Args& a, LAS unsigned char* lds) {
;     ...
;     for (int pr = blockIdx.x; pr < 256; pr += gridDim.x) {
;         const int b = pr >> 4, tt0 = pr & 15;
; #pragma unroll 1
;         for (int it = 0; it < 2; ++it) {
;             const int t = it ? 31 - tt0 : tt0;
;     ...
;                 const bf16_t* Ks = ksl + (size_t)bh * 2048 * 64; const bf16_t* Vs = vslT + (size_t)bh * 64 * 2048;
;                 const bf16_t* Kw = kwn + (size_t)bh * 2048 * 64; const bf16_t* Vw = vwnT + (size_t)bh * 64 * 2048;
.LBB0_713:
	v_writelane_b32 v255, s0, 1
	v_readlane_b32 s2, v254, 45
	s_ashr_i32 s1, s0, 4
	s_cmp_lg_u32 s2, 0x100
	s_cbranch_scc1 .Lattn_nomap
	s_and_b32 s1, s0, 7
	s_lshl_b32 s1, s1, 1
	s_lshr_b32 s2, s0, 7
	s_add_i32 s1, s1, s2
	s_lshr_b32 s0, s0, 3
.Lattn_nomap:
	s_and_b32 s0, s0, 15
	v_writelane_b32 v254, s0, 29
	s_xor_b32 s0, s0, 31
	v_writelane_b32 v254, s0, 30
	s_lshl_b32 s0, s1, 1
	s_lshl_b32 s39, s1, 11
	s_ashr_i32 s1, s0, 31
	s_lshl_b64 s[2:3], s[0:1], 14
	v_readlane_b32 s6, v254, 50
	s_add_u32 s4, s6, s2
	v_readlane_b32 s7, v254, 51
	s_addc_u32 s5, s7, s3
	v_writelane_b32 v254, s4, 39
	s_mov_b64 s[64:65], -1
	s_nop 0
	v_writelane_b32 v254, s5, 40
	s_nop 0
	v_readlane_b32 s8, v254, 52
	s_add_u32 s2, s8, s2
	v_readlane_b32 s9, v254, 53
	s_addc_u32 s3, s9, s3
	v_writelane_b32 v254, s2, 31
	s_lshl_b64 s[4:5], s[0:1], 18
	s_nop 0
	v_writelane_b32 v254, s3, 32
	s_lshl_b64 s[2:3], s[0:1], 17
	s_add_u32 s10, s71, s4
	s_addc_u32 s11, s72, s5
	v_writelane_b32 v254, s10, 41
	s_add_u32 s4, s73, s4
	s_addc_u32 s5, s74, s5
	v_writelane_b32 v254, s11, 42
	s_or_b32 s0, s0, 1
	v_writelane_b32 v254, s4, 33
	s_ashr_i32 s1, s0, 31
	s_nop 0
	v_writelane_b32 v254, s5, 34
	s_lshl_b64 s[4:5], s[0:1], 14
	s_add_u32 s6, s6, s4
	s_addc_u32 s7, s7, s5
	s_add_u32 s52, s8, s4
	s_addc_u32 s53, s9, s5
	s_lshl_b64 s[4:5], s[0:1], 17
	s_lshl_b64 s[0:1], s[0:1], 18
	s_add_u32 s54, s71, s0
	s_addc_u32 s55, s72, s1
	v_writelane_b32 v254, s6, 35
	s_add_u32 s56, s73, s0
	s_addc_u32 s57, s74, s1
	v_writelane_b32 v254, s7, 36
	s_lshl_b64 s[58:59], s[2:3], 1
	s_lshl_b64 s[60:61], s[4:5], 1
	s_branch .LBB0_715

; #define LAS __attribute__((address_space(3)))
; __device__ __forceinline__ void phase4_gmlp(const Args& a, LAS unsigned char* lds) {
;     const int tid0 = threadIdx.x, g = __builtin_amdgcn_readfirstlane(tid0 >> 6);
;     unsigned char* ws = a.ws;
;     const bf16_t* zu = (const bf16_t*)(ws + WS_ZU); const bf16_t* zvT = (const bf16_t*)(ws + WS_ZVT); const bf16_t* Wsp = (const bf16_t*)(ws + WS_WSP);
;     const float* sp_b = a.in[10];
;     bf16_t* o = (bf16_t*)(ws + WS_O);
;     LAS float* SSQ2 = (LAS float*)(lds + G_SSQ);
;     LAS unsigned char* tile = lds + g * G_TILE;
;     for (int item = blockIdx.x; item < 256; item += gridDim.x) {
;         const int b = item >> 4, ch = item & 15;
;         const size_t tok0 = (size_t)b * 2048 + ch * 128;
;         int tid = tid0; asm volatile("" : "+v"(tid));
;         const int lane = tid & 63, r = lane & 31, h = lane >> 5;
.LBB0_875:
	v_readlane_b32 s0, v254, 47
	v_readlane_b32 s1, v254, 48
	v_readlane_b32 s76, v254, 4
	v_readlane_b32 s28, v254, 43
	s_andn2_b64 vcc, exec, s[0:1]
	v_readfirstlane_b32 s4, v184
	v_readlane_b32 s70, v254, 49
	v_readlane_b32 s77, v254, 5
	v_readlane_b32 s78, v254, 6
	v_readlane_b32 s79, v254, 7
	v_readlane_b32 s88, v254, 45
	v_readlane_b32 s29, v254, 44
	v_readlane_b32 s89, v254, 46
	s_cbranch_vccnz .LBB0_886
	s_lshr_b32 s0, s4, 6
	s_add_u32 s2, s78, 0x13600000
	s_addc_u32 s3, s79, 0
	s_and_b32 s6, s4, 0xffffffc0
	s_mul_i32 s1, s0, 0x4400
	s_ashr_i32 s7, s6, 31
	s_add_i32 s14, s1, 0
	s_lshl_b64 s[6:7], s[6:7], 1
	s_add_u32 s4, s78, s6
	s_mov_b32 s5, 0
	s_addc_u32 s9, s79, s7
	s_mov_b32 s1, s5
	s_add_u32 s8, s4, 0x11600000
	s_addc_u32 s9, s9, 0
	s_lshl_b32 s15, s0, 7
	s_lshl_b64 s[10:11], s[0:1], 15
	s_add_u32 s1, s78, s10
	v_mbcnt_lo_u32_b32 v0, -1, 0
	s_addc_u32 s4, s79, s11
	v_mbcnt_hi_u32_b32 v166, -1, v0
	s_add_u32 s10, s1, 0x1ac0000
	v_and_b32_e32 v0, 64, v166
	s_addc_u32 s11, s4, 0
	v_mov_b32_e32 v129, 0
	s_movk_i32 s1, 0x2000
	s_movk_i32 s16, 0x4000
	s_movk_i32 s17, 0x6000
	s_movk_i32 s18, 0x88
	v_mov_b32_e32 v164, 0x1540
	v_mov_b32_e32 v165, 0x2a80
	v_xor_b32_e32 v167, 32, v166
	v_add_u32_e32 v168, 64, v0
	v_mov_b32_e32 v169, 0x358637bd
	s_mov_b32 s19, 0x800000
	s_mov_b32 s20, 0x15600000
	s_add_i32 s21, 0, 0x22000
	s_mov_b32 s22, s70
	s_cmp_lg_u32 s88, 0x100
	s_cbranch_scc1 .Lgm_nomap
	s_and_b32 s22, s70, 7
	s_lshl_b32 s22, s22, 1
	s_lshr_b32 s23, s70, 7
	s_add_i32 s22, s22, s23
	s_lshl_b32 s22, s22, 4
	s_bfe_u32 s23, s70, 0x40003
	s_or_b32 s22, s22, s23
.Lgm_nomap:
	s_branch .LBB0_878

; #define LAS __attribute__((address_space(3)))
; __device__ __forceinline__ unsigned xb_ld(unsigned* p) { return __hip_atomic_load(p, __ATOMIC_RELAXED, __HIP_MEMORY_SCOPE_AGENT); }
; __device__ __forceinline__ unsigned xb_add(unsigned* p, unsigned v) { return __hip_atomic_fetch_add(p, v, __ATOMIC_RELAXED, __HIP_MEMORY_SCOPE_AGENT); }
; __device__ __forceinline__ unsigned xb_xcc_id() { return (unsigned)__builtin_amdgcn_s_getreg((3 << 11) | 20) & 0xFu; }
; __device__ __forceinline__ void grid_barrier(unsigned* barw, int k, volatile LAS unsigned* st) {
;     asm volatile("s_waitcnt vmcnt(0)" ::: "memory");
;     __syncthreads();
;     if (threadIdx.x == 0) {
;         __builtin_amdgcn_s_waitcnt(0);
;         const unsigned x = xb_xcc_id();
;         unsigned nloc = st[0], nx = st[1];
;         if (nloc == 0u) {
;             const unsigned G = gridDim.x;
;             for (;;) { unsigned sum = 0u, cnt = 0u, mine = 0u;
; #pragma unroll
;                 for (unsigned j = 0; j < 16; ++j) { const unsigned c = xb_ld(barw + 64 * j); sum += c; cnt += (c > 0u) ? 1u : 0u; mine = (j == x) ? c : mine; }
;                 if (sum == G) { nloc = mine; nx = cnt; break; }
;                 __builtin_amdgcn_s_sleep(1); }
;             st[0] = nloc; st[1] = nx;
;         }
;         unsigned* sb = barw + 1024 + k * 2304;
;         const unsigned old = xb_add(sb + 64 * x, 1u);
;         if (old + 1u == nloc) {
;             __builtin_amdgcn_fence(__ATOMIC_RELEASE, "agent");
;             asm volatile("s_waitcnt vmcnt(0)" ::: "memory");
;             const unsigned og = xb_add(sb + 2048, 1u);
;             if (og + 1u == nx) xb_add(sb + 2112, 1u);
;             else while (xb_ld(sb + 2112) == 0u) __builtin_amdgcn_s_sleep(1);
;             __builtin_amdgcn_fence(__ATOMIC_ACQUIRE, "agent");
;             xb_add(sb + 1024 + 64 * x, 1u);
;             asm volatile("s_waitcnt vmcnt(0)" ::: "memory");
;         } else {
;             while (xb_ld(sb + 1024 + 64 * x) == 0u) __builtin_amdgcn_s_sleep(1);
;             __builtin_amdgcn_fence(__ATOMIC_ACQUIRE, "agent");
;             asm volatile("s_waitcnt vmcnt(0)" ::: "memory");
;         }
;     }
;     __syncthreads();
; }
.LBB0_886:
	v_readlane_b32 s0, v254, 0
	v_readlane_b32 s1, v254, 1
	s_cmp_gt_i32 s1, 5
	s_cselect_b64 s[72:73], -1, 0
	s_and_b64 s[0:1], s[28:29], s[72:73]
	s_andn2_b64 vcc, exec, s[0:1]
	s_cbranch_vccnz .LBB0_915
	s_waitcnt vmcnt(0)
	s_waitcnt vmcnt(0) lgkmcnt(0)
	s_barrier
	s_mov_b64 s[74:75], exec
	v_readlane_b32 s0, v254, 2
	v_readlane_b32 s1, v254, 3
	s_and_b64 s[0:1], s[74:75], s[0:1]
	s_mov_b64 exec, s[0:1]
	s_cbranch_execz .LBB0_914
	s_cmp_lg_u32 s88, 0x100
	s_cbranch_scc1 .Lgb2_orig
	s_waitcnt vmcnt(0) lgkmcnt(0)
	s_and_b32 s0, s70, 7
	s_lshl_b32 s0, s0, 8
	s_add_i32 s0, s0, 0x11c00
	s_add_u32 s4, s78, s0
	s_addc_u32 s5, s79, 0
	s_lshr_b32 s6, s88, 3
	s_getreg_b32 s8, hwreg(HW_REG_XCC_ID, 0, 4)
	s_lshl_b32 s8, 1, s8
	v_mov_b32_e32 v0, 0
	v_mov_b32_e32 v1, s8
	global_atomic_or v2, v0, v1, s[4:5] offset:64 sc0
	s_waitcnt vmcnt(0)
	v_mov_b32_e32 v1, 1
	global_atomic_add v2, v0, v1, s[4:5] sc0
	s_waitcnt vmcnt(0)
	v_readfirstlane_b32 s7, v2
	s_add_i32 s7, s7, 1
	s_cmp_ge_u32 s7, s6
	s_cbranch_scc1 .Lgb2_all1
